# GEMM residual epilogue (x += acc, bf16 copy): loads batched 8 at a time with counted waits instead of 32 serialized round trips
# baseline (speedup 1.0000x reference)
; __device__ __forceinline__ unsigned cvt_pk_bf16(float lo, float hi) { unsigned r; asm volatile("v_cvt_pk_bf16_f32 %0, %1, %2" : "=v"(r) : "v"(lo), "v"(hi)); return r; }
;     __device__ __forceinline__ void operator()(const f32x4 (&acc)[2][2][4][2], const pg8::Unit& u, int wr, int wc, int fr, int fq) const {
;         const int row0 = u.pm * 256 + wr * 64 + fr, col0 = u.pn * 256 + wc * 32 + 4 * fq;
; #pragma unroll
;         for (int ai = 0; ai < 2; ++ai)
; #pragma unroll
;             for (int m = 0; m < 4; ++m) { float* rowp = X + (size_t)(row0 + ai * 128 + m * 16) * 1024 + col0;
; #pragma unroll
;                 for (int bj = 0; bj < 2; ++bj)
; #pragma unroll
;                     for (int n = 0; n < 2; ++n) { f32x4* p = (f32x4*)(rowp + bj * 128 + n * 16); const f32x4 v = *p + acc[ai][bj][m][n]; *p = v;
;                         u32x2 w; w.x = cvt_pk_bf16(v[0], v[1]); w.y = cvt_pk_bf16(v[2], v[3]);
;                         *(u32x2*)(XB + (size_t)(row0 + ai * 128 + m * 16) * 1024 + col0 + bj * 128 + n * 16) = w; } }
;     }
.LBB0_275:
	v_lshl_add_u32 v150, s15, 8, v154
	v_lshl_or_b32 v180, s14, 8, v156
	v_readlane_b32 s6, v253, 24
	v_readlane_b32 s7, v253, 25
	v_lshlrev_b32_e32 v220, 12, v150
	v_lshl_add_u32 v220, v180, 2, v220
	v_lshrrev_b32_e32 v221, 1, v220
	v_mov_b32_e32 v216, v220
	v_mov_b32_e32 v218, v221
	v_add_u32_e32 v217, 0x10000, v220
	v_add_u32_e32 v219, 0x8000, v221
	global_load_dwordx4 v[184:187], v216, s[88:89] offset:0
	global_load_dwordx4 v[188:191], v216, s[88:89] offset:64
	global_load_dwordx4 v[192:195], v216, s[88:89] offset:512
	global_load_dwordx4 v[196:199], v216, s[88:89] offset:576
	global_load_dwordx4 v[200:203], v217, s[88:89] offset:0
	global_load_dwordx4 v[204:207], v217, s[88:89] offset:64
	global_load_dwordx4 v[208:211], v217, s[88:89] offset:512
	global_load_dwordx4 v[212:215], v217, s[88:89] offset:576
	s_waitcnt vmcnt(7)
	v_pk_add_f32 v[126:127], v[126:127], v[186:187]
	v_pk_add_f32 v[124:125], v[124:125], v[184:185]
	global_store_dwordx4 v216, v[124:127], s[88:89] offset:0
	v_cvt_pk_bf16_f32 v184, v124, v125
	v_cvt_pk_bf16_f32 v185, v126, v127
	global_store_dwordx2 v218, v[184:185], s[6:7] offset:0
	s_waitcnt vmcnt(8)
	v_pk_add_f32 v[122:123], v[122:123], v[190:191]
	v_pk_add_f32 v[120:121], v[120:121], v[188:189]
	global_store_dwordx4 v216, v[120:123], s[88:89] offset:64
	v_cvt_pk_bf16_f32 v188, v120, v121
	v_cvt_pk_bf16_f32 v189, v122, v123
	global_store_dwordx2 v218, v[188:189], s[6:7] offset:32
	s_waitcnt vmcnt(9)
	v_pk_add_f32 v[118:119], v[118:119], v[194:195]
	v_pk_add_f32 v[116:117], v[116:117], v[192:193]
	global_store_dwordx4 v216, v[116:119], s[88:89] offset:512
	v_cvt_pk_bf16_f32 v192, v116, v117
	v_cvt_pk_bf16_f32 v193, v118, v119
	global_store_dwordx2 v218, v[192:193], s[6:7] offset:256
	s_waitcnt vmcnt(10)
	v_pk_add_f32 v[114:115], v[114:115], v[198:199]
	v_pk_add_f32 v[112:113], v[112:113], v[196:197]
	global_store_dwordx4 v216, v[112:115], s[88:89] offset:576
	v_cvt_pk_bf16_f32 v196, v112, v113
	v_cvt_pk_bf16_f32 v197, v114, v115
	global_store_dwordx2 v218, v[196:197], s[6:7] offset:288
	s_waitcnt vmcnt(11)
	v_pk_add_f32 v[110:111], v[110:111], v[202:203]
	v_pk_add_f32 v[108:109], v[108:109], v[200:201]
	global_store_dwordx4 v217, v[108:111], s[88:89] offset:0
	v_cvt_pk_bf16_f32 v200, v108, v109
	v_cvt_pk_bf16_f32 v201, v110, v111
	global_store_dwordx2 v219, v[200:201], s[6:7] offset:0
	s_waitcnt vmcnt(12)
	v_pk_add_f32 v[106:107], v[106:107], v[206:207]
	v_pk_add_f32 v[104:105], v[104:105], v[204:205]
	global_store_dwordx4 v217, v[104:107], s[88:89] offset:64
	v_cvt_pk_bf16_f32 v204, v104, v105
	v_cvt_pk_bf16_f32 v205, v106, v107
	global_store_dwordx2 v219, v[204:205], s[6:7] offset:32
	s_waitcnt vmcnt(13)
	v_pk_add_f32 v[102:103], v[102:103], v[210:211]
	v_pk_add_f32 v[100:101], v[100:101], v[208:209]
	global_store_dwordx4 v217, v[100:103], s[88:89] offset:512
	v_cvt_pk_bf16_f32 v208, v100, v101
	v_cvt_pk_bf16_f32 v209, v102, v103
	global_store_dwordx2 v219, v[208:209], s[6:7] offset:256
	s_waitcnt vmcnt(14)
	v_pk_add_f32 v[98:99], v[98:99], v[214:215]
	v_pk_add_f32 v[96:97], v[96:97], v[212:213]
	global_store_dwordx4 v217, v[96:99], s[88:89] offset:576
	v_cvt_pk_bf16_f32 v212, v96, v97
	v_cvt_pk_bf16_f32 v213, v98, v99
	global_store_dwordx2 v219, v[212:213], s[6:7] offset:288
	v_add_u32_e32 v216, 0x20000, v220
	v_add_u32_e32 v218, 0x10000, v221
	v_add_u32_e32 v217, 0x30000, v220
	v_add_u32_e32 v219, 0x18000, v221
	global_load_dwordx4 v[184:187], v216, s[88:89] offset:0
	global_load_dwordx4 v[188:191], v216, s[88:89] offset:64
	global_load_dwordx4 v[192:195], v216, s[88:89] offset:512
	global_load_dwordx4 v[196:199], v216, s[88:89] offset:576
	global_load_dwordx4 v[200:203], v217, s[88:89] offset:0
	global_load_dwordx4 v[204:207], v217, s[88:89] offset:64
	global_load_dwordx4 v[208:211], v217, s[88:89] offset:512
	global_load_dwordx4 v[212:215], v217, s[88:89] offset:576
	s_waitcnt vmcnt(7)
	v_pk_add_f32 v[94:95], v[94:95], v[186:187]
	v_pk_add_f32 v[92:93], v[92:93], v[184:185]
	global_store_dwordx4 v216, v[92:95], s[88:89] offset:0
	v_cvt_pk_bf16_f32 v184, v92, v93
	v_cvt_pk_bf16_f32 v185, v94, v95
	global_store_dwordx2 v218, v[184:185], s[6:7] offset:0
	s_waitcnt vmcnt(8)
	v_pk_add_f32 v[90:91], v[90:91], v[190:191]
	v_pk_add_f32 v[88:89], v[88:89], v[188:189]
	global_store_dwordx4 v216, v[88:91], s[88:89] offset:64
	v_cvt_pk_bf16_f32 v188, v88, v89
	v_cvt_pk_bf16_f32 v189, v90, v91
	global_store_dwordx2 v218, v[188:189], s[6:7] offset:32
	s_waitcnt vmcnt(9)
	v_pk_add_f32 v[86:87], v[86:87], v[194:195]
	v_pk_add_f32 v[84:85], v[84:85], v[192:193]
	global_store_dwordx4 v216, v[84:87], s[88:89] offset:512
	v_cvt_pk_bf16_f32 v192, v84, v85
	v_cvt_pk_bf16_f32 v193, v86, v87
	global_store_dwordx2 v218, v[192:193], s[6:7] offset:256
	s_waitcnt vmcnt(10)
	v_pk_add_f32 v[82:83], v[82:83], v[198:199]
	v_pk_add_f32 v[80:81], v[80:81], v[196:197]
	global_store_dwordx4 v216, v[80:83], s[88:89] offset:576
	v_cvt_pk_bf16_f32 v196, v80, v81
	v_cvt_pk_bf16_f32 v197, v82, v83
	global_store_dwordx2 v218, v[196:197], s[6:7] offset:288
	s_waitcnt vmcnt(11)
	v_pk_add_f32 v[78:79], v[78:79], v[202:203]
	v_pk_add_f32 v[76:77], v[76:77], v[200:201]
	global_store_dwordx4 v217, v[76:79], s[88:89] offset:0
	v_cvt_pk_bf16_f32 v200, v76, v77
	v_cvt_pk_bf16_f32 v201, v78, v79
	global_store_dwordx2 v219, v[200:201], s[6:7] offset:0
	s_waitcnt vmcnt(12)
	v_pk_add_f32 v[74:75], v[74:75], v[206:207]
	v_pk_add_f32 v[72:73], v[72:73], v[204:205]
	global_store_dwordx4 v217, v[72:75], s[88:89] offset:64
	v_cvt_pk_bf16_f32 v204, v72, v73
	v_cvt_pk_bf16_f32 v205, v74, v75
	global_store_dwordx2 v219, v[204:205], s[6:7] offset:32
	s_waitcnt vmcnt(13)
; __device__ __forceinline__ unsigned cvt_pk_bf16(float lo, float hi) { unsigned r; asm volatile("v_cvt_pk_bf16_f32 %0, %1, %2" : "=v"(r) : "v"(lo), "v"(hi)); return r; }
;     __device__ __forceinline__ void operator()(const f32x4 (&acc)[2][2][4][2], const pg8::Unit& u, int wr, int wc, int fr, int fq) const {
;         const int row0 = u.pm * 256 + wr * 64 + fr, col0 = u.pn * 256 + wc * 32 + 4 * fq;
; #pragma unroll
;         for (int ai = 0; ai < 2; ++ai)
; #pragma unroll
;             for (int m = 0; m < 4; ++m) { float* rowp = X + (size_t)(row0 + ai * 128 + m * 16) * 1024 + col0;
; #pragma unroll
;                 for (int bj = 0; bj < 2; ++bj)
; #pragma unroll
;                     for (int n = 0; n < 2; ++n) { f32x4* p = (f32x4*)(rowp + bj * 128 + n * 16); const f32x4 v = *p + acc[ai][bj][m][n]; *p = v;
;                         u32x2 w; w.x = cvt_pk_bf16(v[0], v[1]); w.y = cvt_pk_bf16(v[2], v[3]);
;                         *(u32x2*)(XB + (size_t)(row0 + ai * 128 + m * 16) * 1024 + col0 + bj * 128 + n * 16) = w; } }
;     }
	v_pk_add_f32 v[70:71], v[70:71], v[210:211]
	v_pk_add_f32 v[68:69], v[68:69], v[208:209]
	global_store_dwordx4 v217, v[68:71], s[88:89] offset:512
	v_cvt_pk_bf16_f32 v208, v68, v69
	v_cvt_pk_bf16_f32 v209, v70, v71
	global_store_dwordx2 v219, v[208:209], s[6:7] offset:256
	s_waitcnt vmcnt(14)
	v_pk_add_f32 v[66:67], v[66:67], v[214:215]
	v_pk_add_f32 v[64:65], v[64:65], v[212:213]
	global_store_dwordx4 v217, v[64:67], s[88:89] offset:576
	v_cvt_pk_bf16_f32 v212, v64, v65
	v_cvt_pk_bf16_f32 v213, v66, v67
	global_store_dwordx2 v219, v[212:213], s[6:7] offset:288
	v_add_u32_e32 v216, 0x80000, v220
	v_add_u32_e32 v218, 0x40000, v221
	v_add_u32_e32 v217, 0x90000, v220
	v_add_u32_e32 v219, 0x48000, v221
	global_load_dwordx4 v[184:187], v216, s[88:89] offset:0
	global_load_dwordx4 v[188:191], v216, s[88:89] offset:64
	global_load_dwordx4 v[192:195], v216, s[88:89] offset:512
	global_load_dwordx4 v[196:199], v216, s[88:89] offset:576
	global_load_dwordx4 v[200:203], v217, s[88:89] offset:0
	global_load_dwordx4 v[204:207], v217, s[88:89] offset:64
	global_load_dwordx4 v[208:211], v217, s[88:89] offset:512
	global_load_dwordx4 v[212:215], v217, s[88:89] offset:576
	s_waitcnt vmcnt(7)
	v_pk_add_f32 v[62:63], v[62:63], v[186:187]
	v_pk_add_f32 v[60:61], v[60:61], v[184:185]
	global_store_dwordx4 v216, v[60:63], s[88:89] offset:0
	v_cvt_pk_bf16_f32 v184, v60, v61
	v_cvt_pk_bf16_f32 v185, v62, v63
	global_store_dwordx2 v218, v[184:185], s[6:7] offset:0
	s_waitcnt vmcnt(8)
	v_pk_add_f32 v[58:59], v[58:59], v[190:191]
	v_pk_add_f32 v[56:57], v[56:57], v[188:189]
	global_store_dwordx4 v216, v[56:59], s[88:89] offset:64
	v_cvt_pk_bf16_f32 v188, v56, v57
	v_cvt_pk_bf16_f32 v189, v58, v59
	global_store_dwordx2 v218, v[188:189], s[6:7] offset:32
	s_waitcnt vmcnt(9)
	v_pk_add_f32 v[54:55], v[54:55], v[194:195]
	v_pk_add_f32 v[52:53], v[52:53], v[192:193]
	global_store_dwordx4 v216, v[52:55], s[88:89] offset:512
	v_cvt_pk_bf16_f32 v192, v52, v53
	v_cvt_pk_bf16_f32 v193, v54, v55
	global_store_dwordx2 v218, v[192:193], s[6:7] offset:256
	s_waitcnt vmcnt(10)
	v_pk_add_f32 v[50:51], v[50:51], v[198:199]
	v_pk_add_f32 v[48:49], v[48:49], v[196:197]
	global_store_dwordx4 v216, v[48:51], s[88:89] offset:576
	v_cvt_pk_bf16_f32 v196, v48, v49
	v_cvt_pk_bf16_f32 v197, v50, v51
	global_store_dwordx2 v218, v[196:197], s[6:7] offset:288
	s_waitcnt vmcnt(11)
	v_pk_add_f32 v[46:47], v[46:47], v[202:203]
	v_pk_add_f32 v[44:45], v[44:45], v[200:201]
	global_store_dwordx4 v217, v[44:47], s[88:89] offset:0
	v_cvt_pk_bf16_f32 v200, v44, v45
	v_cvt_pk_bf16_f32 v201, v46, v47
	global_store_dwordx2 v219, v[200:201], s[6:7] offset:0
	s_waitcnt vmcnt(12)
	v_pk_add_f32 v[42:43], v[42:43], v[206:207]
	v_pk_add_f32 v[40:41], v[40:41], v[204:205]
	global_store_dwordx4 v217, v[40:43], s[88:89] offset:64
	v_cvt_pk_bf16_f32 v204, v40, v41
	v_cvt_pk_bf16_f32 v205, v42, v43
	global_store_dwordx2 v219, v[204:205], s[6:7] offset:32
	s_waitcnt vmcnt(13)
	v_pk_add_f32 v[38:39], v[38:39], v[210:211]
	v_pk_add_f32 v[36:37], v[36:37], v[208:209]
	global_store_dwordx4 v217, v[36:39], s[88:89] offset:512
	v_cvt_pk_bf16_f32 v208, v36, v37
	v_cvt_pk_bf16_f32 v209, v38, v39
	global_store_dwordx2 v219, v[208:209], s[6:7] offset:256
	s_waitcnt vmcnt(14)
	v_pk_add_f32 v[34:35], v[34:35], v[214:215]
	v_pk_add_f32 v[32:33], v[32:33], v[212:213]
	global_store_dwordx4 v217, v[32:35], s[88:89] offset:576
	v_cvt_pk_bf16_f32 v212, v32, v33
	v_cvt_pk_bf16_f32 v213, v34, v35
	global_store_dwordx2 v219, v[212:213], s[6:7] offset:288
	v_add_u32_e32 v216, 0xa0000, v220
	v_add_u32_e32 v218, 0x50000, v221
	v_add_u32_e32 v217, 0xb0000, v220
	v_add_u32_e32 v219, 0x58000, v221
	global_load_dwordx4 v[184:187], v216, s[88:89] offset:0
	global_load_dwordx4 v[188:191], v216, s[88:89] offset:64
	global_load_dwordx4 v[192:195], v216, s[88:89] offset:512
	global_load_dwordx4 v[196:199], v216, s[88:89] offset:576
	global_load_dwordx4 v[200:203], v217, s[88:89] offset:0
	global_load_dwordx4 v[204:207], v217, s[88:89] offset:64
	global_load_dwordx4 v[208:211], v217, s[88:89] offset:512
	global_load_dwordx4 v[212:215], v217, s[88:89] offset:576
	s_waitcnt vmcnt(7)
	v_pk_add_f32 v[30:31], v[30:31], v[186:187]
	v_pk_add_f32 v[28:29], v[28:29], v[184:185]
	global_store_dwordx4 v216, v[28:31], s[88:89] offset:0
	v_cvt_pk_bf16_f32 v184, v28, v29
	v_cvt_pk_bf16_f32 v185, v30, v31
	global_store_dwordx2 v218, v[184:185], s[6:7] offset:0
	s_waitcnt vmcnt(8)
	v_pk_add_f32 v[26:27], v[26:27], v[190:191]
	v_pk_add_f32 v[24:25], v[24:25], v[188:189]
	global_store_dwordx4 v216, v[24:27], s[88:89] offset:64
	v_cvt_pk_bf16_f32 v188, v24, v25
	v_cvt_pk_bf16_f32 v189, v26, v27
	global_store_dwordx2 v218, v[188:189], s[6:7] offset:32
	s_waitcnt vmcnt(9)
	v_pk_add_f32 v[22:23], v[22:23], v[194:195]
	v_pk_add_f32 v[20:21], v[20:21], v[192:193]
	global_store_dwordx4 v216, v[20:23], s[88:89] offset:512
	v_cvt_pk_bf16_f32 v192, v20, v21
	v_cvt_pk_bf16_f32 v193, v22, v23
	global_store_dwordx2 v218, v[192:193], s[6:7] offset:256
	s_waitcnt vmcnt(10)
	v_pk_add_f32 v[18:19], v[18:19], v[198:199]
	v_pk_add_f32 v[16:17], v[16:17], v[196:197]
	global_store_dwordx4 v216, v[16:19], s[88:89] offset:576
	v_cvt_pk_bf16_f32 v196, v16, v17
	v_cvt_pk_bf16_f32 v197, v18, v19
	global_store_dwordx2 v218, v[196:197], s[6:7] offset:288
	s_waitcnt vmcnt(11)
	v_pk_add_f32 v[14:15], v[14:15], v[202:203]
	v_pk_add_f32 v[12:13], v[12:13], v[200:201]
	global_store_dwordx4 v217, v[12:15], s[88:89] offset:0
	v_cvt_pk_bf16_f32 v200, v12, v13
	v_cvt_pk_bf16_f32 v201, v14, v15
	global_store_dwordx2 v219, v[200:201], s[6:7] offset:0
	s_waitcnt vmcnt(12)
	v_pk_add_f32 v[10:11], v[10:11], v[206:207]
	v_pk_add_f32 v[8:9], v[8:9], v[204:205]
	global_store_dwordx4 v217, v[8:11], s[88:89] offset:64
	v_cvt_pk_bf16_f32 v204, v8, v9
	v_cvt_pk_bf16_f32 v205, v10, v11
	global_store_dwordx2 v219, v[204:205], s[6:7] offset:32
	s_waitcnt vmcnt(13)
	v_pk_add_f32 v[6:7], v[6:7], v[210:211]
	v_pk_add_f32 v[4:5], v[4:5], v[208:209]
	global_store_dwordx4 v217, v[4:7], s[88:89] offset:512
	v_cvt_pk_bf16_f32 v208, v4, v5
	v_cvt_pk_bf16_f32 v209, v6, v7
	global_store_dwordx2 v219, v[208:209], s[6:7] offset:256
	s_waitcnt vmcnt(14)
	v_pk_add_f32 v[2:3], v[2:3], v[214:215]
	v_pk_add_f32 v[0:1], v[0:1], v[212:213]
	global_store_dwordx4 v217, v[0:3], s[88:89] offset:576
	v_cvt_pk_bf16_f32 v212, v0, v1
	v_cvt_pk_bf16_f32 v213, v2, v3
	global_store_dwordx2 v219, v[212:213], s[6:7] offset:288
	s_andn2_b64 vcc, exec, s[42:43]
	s_nop 4
	s_mov_b64 s[6:7], -1
	s_cbranch_vccnz .LBB0_264
	s_andn2_b64 vcc, exec, s[0:1]
	s_cbranch_vccnz .LBB0_263
	s_barrier
	s_branch .LBB0_263
